# v48 plus one more iteration of the fast attention loop (t+5<=NT), two fewer tiles in the peeled band code
# baseline (speedup 1.0000x reference)
; __device__ __forceinline__ int otid() { int t = threadIdx.x; asm volatile("" : "+v"(t)); return t; }
; #define WAIT_BAR(N) asm volatile("s_waitcnt vmcnt(" #N ") lgkmcnt(0)\n\ts_barrier":::"memory")
;   #define DMA_K(t,slot) glds16(ksrc+(long)(t)*KVBLK*KVP,(unsigned)__builtin_amdgcn_readfirstlane(kdst+(slot)))
;   #define DMA_V(t,slot) glds16(vsrc+(long)(t)*KVBLK*KVP,(unsigned)__builtin_amdgcn_readfirstlane(vdst+(slot)))
;   #define CMASK(P0,P1,t) do{}while(0)
;   #define CMASK(P0,P1,t) do{}while(0)
;   #define CMASK(P0,P1,t) do{}while(0)
; template<int THRL> __device__ __forceinline__ void attn_unit(const bf16*Qu,const bf16*__restrict__ Kh,const bf16*__restrict__ Vh,bf16*Ou,const int NT,const float shift,char*shm){
;   const int tid=otid(),lane=tid&63,r32=lane&31,hi=lane>>5; const int wid=__builtin_amdgcn_readfirstlane(tid>>6);
;   const bf16*Qw=Qu+(long)wid*QBLK*QP;
;   const unsigned lds0=(unsigned)(uintptr_t)shm;
;   float*wsf=(float*)(shm+LDS_WS)+wid*64;
;   const bf16*ksrc=Kh+(long)lane*KVP+wid*8;
;   const bf16*vsrc=Vh+(long)(16*(wid&3)+(lane>>2))*KVP+(wid>>2)*32+(lane&3)*8;
;   const unsigned kdst=lds0+LDS_K+wid*1024, vdst=lds0+LDS_V+wid*1024;
;     ...
;   const int vb0=(int)(lds0+LDS_V)+((lane>>4)&1)*32+(lane&3)*8+(4*hi+((lane&15)>>2))*64;
;   const char*Kbase=shm+LDS_K; bf16x8 kf[8];
;   const lds_cptr shm3=(lds_cptr)shm; const lds_cptr kp0=shm3+LDS_K+hi*1024+r32*16; const lds_cptr vp0=shm3+LDS_V+((lane>>4)&1)*32+(lane&3)*8+(4*hi+((lane&15)>>2))*64;
;   DMA_K(0,0);DMA_V(0,0);DMA_K(1,SLOTB);
;   bf16x8 qr[4];
;   #pragma unroll
;   for(int d0=0;d0<4;++d0)qr[d0]=*reinterpret_cast<const bf16x8*>(&Qw[(long)r32*QP+d0*16+hi*8]);
;   float mhat=0.f,l_reg=0.f;f32x16 o[2];o[0]=f32x16{};o[1]=f32x16{};f32x16 negm=f32x16{};asm volatile("":"+v"(negm));
;     ...
;   bool resc=false;
;     ...
;   f32x16 pA0,pA1,pB0,pB1;
;   int sl_prev=0,sl_cur=0,sl_next=SLOTB;
;     ...
;   DMA_K(2,2*SLOTB);
;   WAIT_BAR(3);
;   qkt(pA0,pA1,Kbase,qr,negm,r32,hi);asm volatile("s_nop 15\n\ts_nop 7":"+v"(pA0),"+v"(pA1));CMASK(pA0,pA1,0);
;   START(pA0,pA1);
.LBB0_616:
	s_lshl_b32 s4, s84, 1
	s_ashr_i32 s5, s82, 2
	s_add_i32 s6, s4, s5
	v_readlane_b32 s4, v246, 62
	v_readlane_b32 s5, v246, 63
	s_lshl_b64 s[4:5], s[4:5], 11
	s_add_u32 s7, s57, s4
	s_addc_u32 s24, s58, s5
	s_lshl_b32 s4, s82, 6
	s_ashr_i32 s5, s4, 31
	s_lshl_b64 s[48:49], s[4:5], 1
	s_add_u32 s26, s7, s48
	s_addc_u32 s27, s24, s49
	s_mul_hi_i32 s7, s6, 0x208000
	s_mul_i32 s6, s6, 0x208000
	s_add_u32 s4, s59, s6
	s_addc_u32 s5, s60, s7
	v_mov_b32_e32 v42, v216
	s_add_u32 s6, s61, s6
	s_addc_u32 s7, s62, s7
	v_readfirstlane_b32 s69, v42
	s_ashr_i32 s44, s69, 6
	s_ashr_i32 s45, s44, 31
	v_and_b32_e32 v238, 63, v42
	s_lshl_b64 s[24:25], s[44:45], 16
	s_add_u32 s24, s26, s24
	v_lshlrev_b32_e32 v0, 4, v42
	s_addc_u32 s25, s27, s25
	v_lshl_add_u64 v[2:3], s[4:5], 0, v[0:1]
	s_mov_b32 s4, 0
	s_ashr_i32 s5, s4, 31
	v_lshl_add_u64 v[212:213], s[4:5], 1, v[2:3]
	s_lshl_b32 s4, s44, 4
	v_bfe_u32 v0, v42, 2, 4
	v_and_or_b32 v0, s4, 48, v0
	s_ashr_i32 s4, s69, 3
	s_andn2_b32 s4, s4, 31
	v_lshlrev_b32_e32 v0, 7, v0
	s_ashr_i32 s5, s4, 31
	s_lshl_b32 s70, s44, 10
	v_lshl_add_u64 v[2:3], s[6:7], 0, v[0:1]
	v_lshlrev_b32_e32 v239, 3, v42
	s_cmp_lg_u32 0, -1
	v_lshl_add_u64 v[2:3], s[4:5], 1, v[2:3]
	v_and_b32_e32 v242, 24, v239
	s_cselect_b32 s4, 0, 0
	v_and_b32_e32 v240, 31, v42
	v_lshlrev_b32_e32 v0, 4, v42
	s_add_i32 s70, s70, s4
	s_mov_b32 s4, m0
	s_mov_b32 m0, s70
	s_nop 0
	global_load_lds_dwordx4 v[212:213], off
	s_mov_b32 m0, s4
	v_bfe_u32 v241, v42, 5, 1
	v_lshl_add_u64 v[214:215], s[6:7], 0, v[0:1]
	s_add_i32 s71, s70, 0x6000
	s_mov_b32 s4, m0
	s_mov_b32 m0, s71
	s_nop 0
	global_load_lds_dwordx4 v[214:215], off
	s_mov_b32 m0, s4
	s_mov_b64 s[26:27], 0x2000
	v_lshlrev_b32_e32 v0, 11, v240
	v_lshl_add_u64 v[2:3], v[212:213], 0, s[26:27]
	s_add_i32 s4, s70, 0x2000
	s_mov_b32 s5, m0
	s_mov_b32 m0, s4
	s_nop 0
	global_load_lds_dwordx4 v[2:3], off
	s_mov_b32 m0, s5
	v_lshl_or_b32 v0, v241, 4, v0
	global_load_dwordx4 v[150:153], v0, s[24:25]
	global_load_dwordx4 v[138:141], v0, s[24:25] offset:32
	global_load_dwordx4 v[134:137], v0, s[24:25] offset:64
	global_load_dwordx4 v[130:133], v0, s[24:25] offset:96
	v_mov_b32_e32 v2, v1
	v_mov_b32_e32 v3, v1
	v_mov_b32_e32 v4, v1
	v_mov_b32_e32 v5, v1
	v_mov_b32_e32 v6, v1
	v_mov_b32_e32 v7, v1
	v_mov_b32_e32 v8, v1
	v_mov_b32_e32 v9, v1
	v_mov_b32_e32 v10, v1
	v_mov_b32_e32 v11, v1
	v_mov_b32_e32 v12, v1
	v_mov_b32_e32 v13, v1
	v_mov_b32_e32 v14, v1
	v_mov_b32_e32 v15, v1
	v_lshlrev_b32_e32 v0, 10, v241
	v_lshlrev_b32_e32 v16, 4, v240
	v_add3_u32 v244, 0, v0, v16
	v_mov_b32_e32 v0, v1
	v_mov_b64_e32 v[16:17], v[14:15]
	v_mov_b64_e32 v[14:15], v[12:13]
	v_mov_b64_e32 v[12:13], v[10:11]
	v_mov_b64_e32 v[10:11], v[8:9]
	v_mov_b64_e32 v[8:9], v[6:7]
	v_mov_b64_e32 v[6:7], v[4:5]
	v_mov_b64_e32 v[4:5], v[2:3]
	v_mov_b64_e32 v[2:3], v[0:1]
	v_lshl_add_u64 v[18:19], v[212:213], 0, s[72:73]
	s_add_i32 s4, s70, 0x4000
	s_mov_b32 s5, m0
	s_mov_b32 m0, s4
	s_nop 0
	global_load_lds_dwordx4 v[18:19], off
	s_mov_b32 m0, s5
	s_waitcnt vmcnt(3) lgkmcnt(0)
	s_barrier
	ds_read_b128 v[34:37], v244
	ds_read_b128 v[38:41], v244 offset:512
	v_lshlrev_b32_e32 v0, 1, v42
	v_and_b32_e32 v243, 32, v0
	s_mov_b64 s[34:35], 0x6000
	v_add_u32_e32 v50, 0, v243
	s_mov_b32 s5, 1
	s_mov_b32 s4, 0
	s_movk_i32 s31, 0x2000
	s_mov_b32 s24, 0
	s_movk_i32 s76, 0x4000
	s_waitcnt vmcnt(3) lgkmcnt(1)
	v_mfma_f32_32x32x16_bf16 v[18:33], v[34:37], v[150:153], v[2:17]
	s_waitcnt lgkmcnt(0)
	v_mfma_f32_32x32x16_bf16 v[2:17], v[38:41], v[150:153], v[2:17]
	ds_read_b128 v[34:37], v244 offset:2048
	ds_read_b128 v[38:41], v244 offset:2560
	s_waitcnt vmcnt(2) lgkmcnt(1)
	v_mfma_f32_32x32x16_bf16 v[18:33], v[34:37], v[138:141], v[18:33]
	s_waitcnt lgkmcnt(0)
	v_mfma_f32_32x32x16_bf16 v[2:17], v[38:41], v[138:141], v[2:17]
	ds_read_b128 v[34:37], v244 offset:4096
	ds_read_b128 v[38:41], v244 offset:4608
	s_waitcnt vmcnt(1) lgkmcnt(1)
	v_mfma_f32_32x32x16_bf16 v[18:33], v[34:37], v[134:137], v[18:33]
	ds_read_b128 v[34:37], v244 offset:6144
	s_waitcnt lgkmcnt(1)
	v_mfma_f32_32x32x16_bf16 v[2:17], v[38:41], v[134:137], v[2:17]
	ds_read_b128 v[38:41], v244 offset:6656
	s_waitcnt vmcnt(0) lgkmcnt(1)
	v_mfma_f32_32x32x16_bf16 v[18:33], v[34:37], v[130:133], v[18:33]
	v_add_f32_e32 v34, v1, v237
	v_lshlrev_b32_e32 v35, 4, v42
	v_xor_b32_e32 v34, 0x80000000, v34
	v_and_b32_e32 v0, 0xc0, v35
	v_mov_b32_e32 v35, v34
	v_mov_b32_e32 v36, v34
	v_mov_b32_e32 v37, v34
	s_waitcnt lgkmcnt(0)
	v_mfma_f32_32x32x16_bf16 v[2:17], v[38:41], v[130:133], v[2:17]
	s_nop 15
	s_nop 7
	v_mov_b32_e32 v38, v34
	v_mov_b32_e32 v39, v34
	v_mov_b32_e32 v40, v34
	v_mov_b32_e32 v41, v34
	v_mov_b32_e32 v42, v34
	v_mov_b32_e32 v43, v34
	v_mov_b32_e32 v44, v34
	v_mov_b32_e32 v45, v34
	v_mov_b32_e32 v46, v34
	v_mov_b32_e32 v47, v34
	v_mov_b32_e32 v48, v34
	v_mov_b32_e32 v49, v34
	v_sub_f32_e32 v2, v2, v237
	v_sub_f32_e32 v3, v3, v237
	s_waitcnt vmcnt(0) lgkmcnt(0)
	s_barrier
; #define WAIT_BAR(N) asm volatile("s_waitcnt vmcnt(" #N ") lgkmcnt(0)\n\ts_barrier":::"memory")
;   #define DMA_K(t,slot) glds16(ksrc+(long)(t)*KVBLK*KVP,(unsigned)__builtin_amdgcn_readfirstlane(kdst+(slot)))
;   #define DMA_V(t,slot) glds16(vsrc+(long)(t)*KVBLK*KVP,(unsigned)__builtin_amdgcn_readfirstlane(vdst+(slot)))
;   #define ROT() do{sl_prev=sl_cur;sl_cur=sl_next;sl_next=(sl_next==(NSLOT-1)*SLOTB)?0:sl_next+SLOTB;}while(0)
; template<int THRL> __device__ __forceinline__ void attn_unit(const bf16*Qu,const bf16*__restrict__ Kh,const bf16*__restrict__ Vh,bf16*Ou,const int NT,const float shift,char*shm){
;     ...
;   _Pragma("unroll") for(int r=0;r<16;++r)pA1[r]=__builtin_amdgcn_exp2f(pA1[r]);
;   WAIT_BAR(0);
;   DMA_K(3,0);DMA_V(1,SLOTB);
;   ROT();
;   kload8(kf,kp0+sl_cur);
;   WAIT_BAR(2);
;     ...
;   int t=1;
;     ...
;   for(;t+5<NT;t+=2){
	v_sub_f32_e32 v18, v18, v237
	v_sub_f32_e32 v19, v19, v237
	s_nop 0
	v_exp_f32_e32 v66, v2
	v_exp_f32_e32 v67, v3
	v_lshl_add_u64 v[2:3], v[212:213], 0, s[34:35]
	s_mov_b32 s6, m0
	s_mov_b32 m0, s70
	s_nop 0
	global_load_lds_dwordx4 v[2:3], off
	s_mov_b32 m0, s6
	v_lshl_add_u64 v[2:3], v[214:215], 0, s[26:27]
	s_add_i32 s6, s70, 0x8000
	s_mov_b32 s7, m0
	s_mov_b32 m0, s6
	s_nop 0
	global_load_lds_dwordx4 v[2:3], off
	s_mov_b32 m0, s7
	ds_read_b128 v[190:193], v244 offset:8192
	ds_read_b128 v[186:189], v244 offset:8704
	ds_read_b128 v[182:185], v244 offset:10240
	ds_read_b128 v[178:181], v244 offset:10752
	ds_read_b128 v[174:177], v244 offset:12288
	ds_read_b128 v[170:173], v244 offset:12800
	ds_read_b128 v[166:169], v244 offset:14336
	ds_read_b128 v[162:165], v244 offset:14848
	v_sub_f32_e32 v20, v20, v237
	v_sub_f32_e32 v4, v4, v237
	v_sub_f32_e32 v21, v21, v237
	v_sub_f32_e32 v5, v5, v237
	v_sub_f32_e32 v22, v22, v237
	v_sub_f32_e32 v6, v6, v237
	v_sub_f32_e32 v23, v23, v237
	v_sub_f32_e32 v7, v7, v237
	v_sub_f32_e32 v24, v24, v237
	v_sub_f32_e32 v8, v8, v237
	v_sub_f32_e32 v25, v25, v237
	v_sub_f32_e32 v9, v9, v237
	v_sub_f32_e32 v26, v26, v237
	v_sub_f32_e32 v10, v10, v237
	v_sub_f32_e32 v27, v27, v237
	v_sub_f32_e32 v11, v11, v237
	v_sub_f32_e32 v28, v28, v237
	v_sub_f32_e32 v12, v12, v237
	v_sub_f32_e32 v29, v29, v237
	v_sub_f32_e32 v13, v13, v237
	v_sub_f32_e32 v30, v30, v237
	v_sub_f32_e32 v14, v14, v237
	v_sub_f32_e32 v31, v31, v237
	v_sub_f32_e32 v15, v15, v237
	v_sub_f32_e32 v32, v32, v237
	v_sub_f32_e32 v16, v16, v237
	v_sub_f32_e32 v33, v33, v237
	v_sub_f32_e32 v17, v17, v237
	v_exp_f32_e32 v82, v18
	v_exp_f32_e32 v83, v19
	v_exp_f32_e32 v84, v20
	v_exp_f32_e32 v85, v21
	v_exp_f32_e32 v86, v22
	v_exp_f32_e32 v87, v23
	v_exp_f32_e32 v88, v24
	v_exp_f32_e32 v89, v25
	v_exp_f32_e32 v90, v26
	v_exp_f32_e32 v91, v27
	v_exp_f32_e32 v92, v28
	v_exp_f32_e32 v93, v29
	v_exp_f32_e32 v94, v30
	v_exp_f32_e32 v95, v31
	v_exp_f32_e32 v96, v32
	v_exp_f32_e32 v97, v33
	v_exp_f32_e32 v68, v4
	v_exp_f32_e32 v69, v5
	v_exp_f32_e32 v70, v6
	v_exp_f32_e32 v71, v7
	v_exp_f32_e32 v72, v8
	v_exp_f32_e32 v73, v9
	v_exp_f32_e32 v74, v10
	v_exp_f32_e32 v75, v11
	v_exp_f32_e32 v76, v12
	v_exp_f32_e32 v77, v13
	v_exp_f32_e32 v78, v14
	v_exp_f32_e32 v79, v15
	v_exp_f32_e32 v80, v16
	v_exp_f32_e32 v81, v17
	s_waitcnt vmcnt(2) lgkmcnt(0)
	s_barrier
	v_lshl_or_b32 v0, v241, 8, v0
	v_add3_u32 v245, v50, v242, v0
	s_cmp_lt_i32 s91, 6
	s_cbranch_scc1 .LBB0_620
	s_mov_b64 s[4:5], 0xa000
	v_mov_b32_e32 v199, v245
	v_add_u32_e32 v200, 0x2000, v245
	v_add_u32_e32 v201, 0x4000, v245
	v_mov_b32_e32 v202, v244
	v_add_u32_e32 v203, 0x2000, v244
	v_add_u32_e32 v204, 0x4000, v244
	v_mov_b32_e32 v50, 0
	v_mov_b32_e32 v194, 0
	v_mov_b32_e32 v195, 0
	v_mov_b32_e32 v196, 0
	v_lshlrev_b32_e32 v197, 4, v238
	v_readfirstlane_b32 s98, v212
	v_readfirstlane_b32 s99, v213
	v_readfirstlane_b32 s100, v214
	v_readfirstlane_b32 s101, v215
	s_add_u32 s98, s98, 0x8000
	s_addc_u32 s99, s99, 0
	s_add_u32 s100, s100, 0x4000
	s_addc_u32 s101, s101, 0
	s_mov_b32 s26, 6
	v_mov_b32_e32 v2, 0
	v_mov_b32_e32 v3, v50
	v_mov_b32_e32 v4, v50
	v_mov_b32_e32 v5, v50
	v_mov_b32_e32 v6, v50
	v_mov_b32_e32 v7, v50
	v_mov_b32_e32 v8, v50
	v_mov_b32_e32 v9, v50
	v_mov_b32_e32 v10, v50
	v_mov_b32_e32 v11, v50
	v_mov_b32_e32 v12, v50
	v_mov_b32_e32 v13, v50
	v_mov_b32_e32 v14, v50
	v_mov_b32_e32 v15, v50
	v_mov_b32_e32 v16, v50
	v_mov_b32_e32 v17, v50
	v_mov_b32_e32 v18, 0
	v_mov_b32_e32 v19, v50
	v_mov_b32_e32 v20, v50
	v_mov_b32_e32 v21, v50
	v_mov_b32_e32 v22, v50
	v_mov_b32_e32 v23, v50
	v_mov_b32_e32 v24, v50
	v_mov_b32_e32 v25, v50
	v_mov_b32_e32 v26, v50
	v_mov_b32_e32 v27, v50
	v_mov_b32_e32 v28, v50
	v_mov_b32_e32 v29, v50
	v_mov_b32_e32 v30, v50
	v_mov_b32_e32 v31, v50
	v_mov_b32_e32 v32, v50
	v_mov_b32_e32 v33, v50
	s_branch .LBB0_618

.LBB0_618:
	s_mov_b32 s4, s76
	s_mov_b32 s5, s26
	s_mov_b32 s25, s31
	ds_read_b64_tr_b16 v[52:53], v199 offset:24576
	ds_read_b64_tr_b16 v[54:55], v199 offset:25088
	v_mfma_f32_32x32x16_bf16 v[114:129], v[190:193], v[150:153], v[34:49]
	v_add_f32_e32 v50, v82, v50
	v_add_f32_e32 v194, v83, v194
	v_add_f32_e32 v195, v84, v195
	v_add_f32_e32 v196, v85, v196
	v_add_f32_e32 v50, v86, v50
	v_add_f32_e32 v194, v87, v194
	v_cvt_pk_bf16_f32 v158, v82, v83
	v_cvt_pk_bf16_f32 v159, v84, v85
	ds_read_b64_tr_b16 v[60:61], v199 offset:28672
	ds_read_b64_tr_b16 v[62:63], v199 offset:29184
	v_mfma_f32_32x32x16_bf16 v[98:113], v[186:189], v[150:153], v[34:49]
	v_add_f32_e32 v195, v88, v195
	v_add_f32_e32 v196, v89, v196
	v_add_f32_e32 v50, v90, v50
	v_add_f32_e32 v194, v91, v194
	v_cvt_pk_bf16_f32 v160, v86, v87
	v_cvt_pk_bf16_f32 v161, v88, v89
	ds_read_b64_tr_b16 v[82:83], v199 offset:25600
	ds_read_b64_tr_b16 v[84:85], v199 offset:26112
	v_mfma_f32_32x32x16_bf16 v[114:129], v[182:185], v[138:141], v[114:129]
	v_add_f32_e32 v195, v92, v195
	v_add_f32_e32 v196, v93, v196
	v_add_f32_e32 v50, v94, v50
	v_add_f32_e32 v194, v95, v194
	v_cvt_pk_bf16_f32 v154, v90, v91
	v_cvt_pk_bf16_f32 v155, v92, v93
	ds_read_b64_tr_b16 v[86:87], v199 offset:29696
	ds_read_b64_tr_b16 v[88:89], v199 offset:30208
	v_mfma_f32_32x32x16_bf16 v[98:113], v[178:181], v[138:141], v[98:113]
	v_add_f32_e32 v195, v96, v195
	v_add_f32_e32 v196, v97, v196
	v_add_f32_e32 v50, v66, v50
	v_add_f32_e32 v194, v67, v194
	v_cvt_pk_bf16_f32 v156, v94, v95
	v_cvt_pk_bf16_f32 v157, v96, v97
	ds_read_b64_tr_b16 v[90:91], v199 offset:26624
	ds_read_b64_tr_b16 v[92:93], v199 offset:27136
	v_mfma_f32_32x32x16_bf16 v[114:129], v[174:177], v[134:137], v[114:129]
	v_add_f32_e32 v195, v68, v195
	v_add_f32_e32 v196, v69, v196
	v_add_f32_e32 v50, v70, v50
	v_add_f32_e32 v194, v71, v194
	v_cvt_pk_bf16_f32 v146, v66, v67
	v_cvt_pk_bf16_f32 v147, v68, v69
	ds_read_b64_tr_b16 v[64:65], v199 offset:30720
	ds_read_b64_tr_b16 v[66:67], v199 offset:31232
	v_mfma_f32_32x32x16_bf16 v[98:113], v[170:173], v[134:137], v[98:113]
	v_add_f32_e32 v195, v72, v195
	v_add_f32_e32 v196, v73, v196
	v_add_f32_e32 v50, v74, v50
	v_add_f32_e32 v194, v75, v194
	v_cvt_pk_bf16_f32 v148, v70, v71
	v_cvt_pk_bf16_f32 v149, v72, v73
	ds_read_b64_tr_b16 v[68:69], v199 offset:27648
	ds_read_b64_tr_b16 v[70:71], v199 offset:28160
	v_mfma_f32_32x32x16_bf16 v[114:129], v[166:169], v[130:133], v[114:129]
	v_add_f32_e32 v195, v76, v195
	v_add_f32_e32 v196, v77, v196
	v_add_f32_e32 v50, v78, v50
	v_add_f32_e32 v194, v79, v194
	v_cvt_pk_bf16_f32 v142, v74, v75
	v_cvt_pk_bf16_f32 v143, v76, v77
	ds_read_b64_tr_b16 v[72:73], v199 offset:31744
	ds_read_b64_tr_b16 v[74:75], v199 offset:32256
	v_mfma_f32_32x32x16_bf16 v[98:113], v[162:165], v[130:133], v[98:113]
	v_add_f32_e32 v195, v80, v195
	v_add_f32_e32 v196, v81, v196
	v_cvt_pk_bf16_f32 v144, v78, v79
	v_cvt_pk_bf16_f32 v145, v80, v81
	s_add_i32 s6, s31, s70
	s_mov_b32 s7, m0
	s_mov_b32 m0, s6
	s_nop 0
	global_load_lds_dwordx4 v197, s[98:99]
	s_mov_b32 m0, s7
	s_add_i32 s6, s76, s71
	s_mov_b32 s7, m0
	s_mov_b32 m0, s6
	s_nop 0
	global_load_lds_dwordx4 v197, s[100:101]
	s_mov_b32 m0, s7
	s_add_u32 s98, s98, 0x2000
	s_addc_u32 s99, s99, 0
	s_add_u32 s100, s100, 0x2000
	s_addc_u32 s101, s101, 0
	s_waitcnt lgkmcnt(14)
	v_mfma_f32_32x32x16_bf16 v[2:17], v[158:161], v[52:55], v[2:17]
	v_exp_f32_e32 v114, v114
	v_exp_f32_e32 v115, v115
	v_exp_f32_e32 v116, v116
	v_exp_f32_e32 v117, v117
	s_waitcnt lgkmcnt(12)
	v_mfma_f32_32x32x16_bf16 v[18:33], v[158:161], v[60:63], v[18:33]
	v_exp_f32_e32 v118, v118
	v_exp_f32_e32 v119, v119
	v_exp_f32_e32 v120, v120
	v_exp_f32_e32 v121, v121
	ds_read_b128 v[60:63], v204
	ds_read_b128 v[162:165], v204 offset:512
	s_waitcnt lgkmcnt(12)
	v_mfma_f32_32x32x16_bf16 v[2:17], v[154:157], v[82:85], v[2:17]
	v_exp_f32_e32 v122, v122
	v_exp_f32_e32 v123, v123
	v_exp_f32_e32 v124, v124
	v_exp_f32_e32 v125, v125
	ds_read_b128 v[166:169], v204 offset:2048
	ds_read_b128 v[170:173], v204 offset:2560
	s_waitcnt lgkmcnt(12)
	v_mfma_f32_32x32x16_bf16 v[18:33], v[154:157], v[86:89], v[18:33]
	v_exp_f32_e32 v126, v126
	v_exp_f32_e32 v127, v127
	v_exp_f32_e32 v128, v128
	v_exp_f32_e32 v129, v129
	ds_read_b128 v[174:177], v204 offset:4096
	ds_read_b128 v[178:181], v204 offset:4608
	s_waitcnt lgkmcnt(12)
	v_mfma_f32_32x32x16_bf16 v[2:17], v[146:149], v[90:93], v[2:17]
	v_exp_f32_e32 v98, v98
	v_exp_f32_e32 v99, v99
	v_exp_f32_e32 v100, v100
	v_exp_f32_e32 v101, v101
	ds_read_b128 v[182:185], v204 offset:6144
	ds_read_b128 v[52:55], v204 offset:6656
	s_waitcnt lgkmcnt(12)
	v_mfma_f32_32x32x16_bf16 v[18:33], v[146:149], v[64:67], v[18:33]
	v_exp_f32_e32 v102, v102
	v_exp_f32_e32 v103, v103
	v_exp_f32_e32 v104, v104
	v_exp_f32_e32 v105, v105
	s_waitcnt lgkmcnt(10)
	v_mfma_f32_32x32x16_bf16 v[2:17], v[142:145], v[68:71], v[2:17]
	v_exp_f32_e32 v106, v106
	v_exp_f32_e32 v107, v107
	v_exp_f32_e32 v108, v108
	v_exp_f32_e32 v109, v109
	s_waitcnt lgkmcnt(8)
	v_mfma_f32_32x32x16_bf16 v[18:33], v[142:145], v[72:75], v[18:33]
	v_exp_f32_e32 v110, v110
	v_exp_f32_e32 v111, v111
	v_exp_f32_e32 v112, v112
	v_exp_f32_e32 v113, v113
	s_waitcnt vmcnt(2) lgkmcnt(0)
	s_barrier
; #define WAIT_BAR(N) asm volatile("s_waitcnt vmcnt(" #N ") lgkmcnt(0)\n\ts_barrier":::"memory")
;   #define RESC() do{ if(resc){ asm volatile("s_waitcnt lgkmcnt(0)":::"memory"); \
;       _Pragma("unroll") for(int d_=0;d_<2;++d_) _Pragma("unroll") for(int r=0;r<16;++r)o[d_][r]*=wsf[crow(r,hi)]; } }while(0)
;   #define ROT() do{sl_prev=sl_cur;sl_cur=sl_next;sl_next=(sl_next==(NSLOT-1)*SLOTB)?0:sl_next+SLOTB;}while(0)
; template<int THRL> __device__ __forceinline__ void attn_unit(const bf16*Qu,const bf16*__restrict__ Kh,const bf16*__restrict__ Vh,bf16*Ou,const int NT,const float shift,char*shm){
;     ...
;   int t=1;
;     ...
;   for(;t+5<NT;t+=2){
;     STEP(pB0,pB1,pA0,pA1,t,true,true,true);     WAIT_BAR(2); RESC(); ROT();
	s_add_i32 s6, s76, 0x2000
	s_cmpk_lg_i32 s76, 0x4000
	s_cselect_b32 s31, s6, 0
	ds_read_b64_tr_b16 v[186:187], v200 offset:24576
	ds_read_b64_tr_b16 v[188:189], v200 offset:25088
	v_mfma_f32_32x32x16_bf16 v[82:97], v[60:63], v[150:153], v[34:49]
	v_add_f32_e32 v50, v114, v50
	v_add_f32_e32 v194, v115, v194
	v_add_f32_e32 v195, v116, v195
	v_add_f32_e32 v196, v117, v196
	v_add_f32_e32 v50, v118, v50
	v_add_f32_e32 v194, v119, v194
	v_cvt_pk_bf16_f32 v158, v114, v115
	v_cvt_pk_bf16_f32 v159, v116, v117
	ds_read_b64_tr_b16 v[60:61], v200 offset:28672
	ds_read_b64_tr_b16 v[62:63], v200 offset:29184
	v_mfma_f32_32x32x16_bf16 v[66:81], v[162:165], v[150:153], v[34:49]
	v_add_f32_e32 v195, v120, v195
	v_add_f32_e32 v196, v121, v196
	v_add_f32_e32 v50, v122, v50
	v_add_f32_e32 v194, v123, v194
	v_cvt_pk_bf16_f32 v160, v118, v119
	v_cvt_pk_bf16_f32 v161, v120, v121
	ds_read_b64_tr_b16 v[114:115], v200 offset:25600
	ds_read_b64_tr_b16 v[116:117], v200 offset:26112
	v_mfma_f32_32x32x16_bf16 v[82:97], v[166:169], v[138:141], v[82:97]
	v_add_f32_e32 v195, v124, v195
	v_add_f32_e32 v196, v125, v196
	v_add_f32_e32 v50, v126, v50
	v_add_f32_e32 v194, v127, v194
	v_cvt_pk_bf16_f32 v154, v122, v123
	v_cvt_pk_bf16_f32 v155, v124, v125
	ds_read_b64_tr_b16 v[118:119], v200 offset:29696
	ds_read_b64_tr_b16 v[120:121], v200 offset:30208
	v_mfma_f32_32x32x16_bf16 v[66:81], v[170:173], v[138:141], v[66:81]
	v_add_f32_e32 v195, v128, v195
	v_add_f32_e32 v196, v129, v196
	v_add_f32_e32 v50, v98, v50
	v_add_f32_e32 v194, v99, v194
	v_cvt_pk_bf16_f32 v156, v126, v127
	v_cvt_pk_bf16_f32 v157, v128, v129
	ds_read_b64_tr_b16 v[122:123], v200 offset:26624
	ds_read_b64_tr_b16 v[124:125], v200 offset:27136
	v_mfma_f32_32x32x16_bf16 v[82:97], v[174:177], v[134:137], v[82:97]
	v_add_f32_e32 v195, v100, v195
	v_add_f32_e32 v196, v101, v196
	v_add_f32_e32 v50, v102, v50
	v_add_f32_e32 v194, v103, v194
	v_cvt_pk_bf16_f32 v146, v98, v99
	v_cvt_pk_bf16_f32 v147, v100, v101
	ds_read_b64_tr_b16 v[98:99], v200 offset:30720
	ds_read_b64_tr_b16 v[100:101], v200 offset:31232
	v_mfma_f32_32x32x16_bf16 v[66:81], v[178:181], v[134:137], v[66:81]
	v_add_f32_e32 v195, v104, v195
	v_add_f32_e32 v196, v105, v196
	v_add_f32_e32 v50, v106, v50
	v_add_f32_e32 v194, v107, v194
	v_cvt_pk_bf16_f32 v148, v102, v103
	v_cvt_pk_bf16_f32 v149, v104, v105
	ds_read_b64_tr_b16 v[102:103], v200 offset:27648
	ds_read_b64_tr_b16 v[104:105], v200 offset:28160
	v_mfma_f32_32x32x16_bf16 v[82:97], v[182:185], v[130:133], v[82:97]
	v_add_f32_e32 v195, v108, v195
	v_add_f32_e32 v196, v109, v196
	v_add_f32_e32 v50, v110, v50
	v_add_f32_e32 v194, v111, v194
	v_cvt_pk_bf16_f32 v142, v106, v107
	v_cvt_pk_bf16_f32 v143, v108, v109
	ds_read_b64_tr_b16 v[106:107], v200 offset:31744
	ds_read_b64_tr_b16 v[108:109], v200 offset:32256
	v_mfma_f32_32x32x16_bf16 v[66:81], v[52:55], v[130:133], v[66:81]
	v_add_f32_e32 v195, v112, v195
	v_add_f32_e32 v196, v113, v196
	v_cvt_pk_bf16_f32 v144, v110, v111
	v_cvt_pk_bf16_f32 v145, v112, v113
	s_add_i32 s6, s76, s70
	s_mov_b32 s7, m0
	s_mov_b32 m0, s6
	s_nop 0
	global_load_lds_dwordx4 v197, s[98:99]
	s_mov_b32 m0, s7
	s_add_i32 s6, s31, s71
	s_mov_b32 s7, m0
	s_mov_b32 m0, s6
	s_nop 0
	global_load_lds_dwordx4 v197, s[100:101]
	s_mov_b32 m0, s7
	s_add_u32 s98, s98, 0x2000
	s_addc_u32 s99, s99, 0
	s_add_u32 s100, s100, 0x2000
	s_addc_u32 s101, s101, 0
	s_waitcnt lgkmcnt(14)
	v_mfma_f32_32x32x16_bf16 v[2:17], v[158:161], v[186:189], v[2:17]
	v_exp_f32_e32 v82, v82
	v_exp_f32_e32 v83, v83
	v_exp_f32_e32 v84, v84
	v_exp_f32_e32 v85, v85
	s_waitcnt lgkmcnt(12)
	v_mfma_f32_32x32x16_bf16 v[18:33], v[158:161], v[60:63], v[18:33]
	v_exp_f32_e32 v86, v86
	v_exp_f32_e32 v87, v87
	v_exp_f32_e32 v88, v88
	v_exp_f32_e32 v89, v89
	ds_read_b128 v[190:193], v202
	ds_read_b128 v[186:189], v202 offset:512
	s_waitcnt lgkmcnt(12)
	v_mfma_f32_32x32x16_bf16 v[2:17], v[154:157], v[114:117], v[2:17]
	v_exp_f32_e32 v90, v90
	v_exp_f32_e32 v91, v91
	v_exp_f32_e32 v92, v92
	v_exp_f32_e32 v93, v93
	ds_read_b128 v[182:185], v202 offset:2048
	ds_read_b128 v[178:181], v202 offset:2560
	s_waitcnt lgkmcnt(12)
	v_mfma_f32_32x32x16_bf16 v[18:33], v[154:157], v[118:121], v[18:33]
	v_exp_f32_e32 v94, v94
	v_exp_f32_e32 v95, v95
	v_exp_f32_e32 v96, v96
	v_exp_f32_e32 v97, v97
	ds_read_b128 v[174:177], v202 offset:4096
	ds_read_b128 v[170:173], v202 offset:4608
	s_waitcnt lgkmcnt(12)
	v_mfma_f32_32x32x16_bf16 v[2:17], v[146:149], v[122:125], v[2:17]
	v_exp_f32_e32 v66, v66
	v_exp_f32_e32 v67, v67
	v_exp_f32_e32 v68, v68
	v_exp_f32_e32 v69, v69
	ds_read_b128 v[166:169], v202 offset:6144
	ds_read_b128 v[162:165], v202 offset:6656
	s_waitcnt lgkmcnt(12)
	v_mfma_f32_32x32x16_bf16 v[18:33], v[146:149], v[98:101], v[18:33]
	v_exp_f32_e32 v70, v70
	v_exp_f32_e32 v71, v71
	v_exp_f32_e32 v72, v72
	v_exp_f32_e32 v73, v73
	s_waitcnt lgkmcnt(10)
	v_mfma_f32_32x32x16_bf16 v[2:17], v[142:145], v[102:105], v[2:17]
	v_exp_f32_e32 v74, v74
	v_exp_f32_e32 v75, v75
	v_exp_f32_e32 v76, v76
	v_exp_f32_e32 v77, v77
	s_waitcnt lgkmcnt(8)
	v_mfma_f32_32x32x16_bf16 v[18:33], v[142:145], v[106:109], v[18:33]
	v_exp_f32_e32 v78, v78
	v_exp_f32_e32 v79, v79
	v_exp_f32_e32 v80, v80
	v_exp_f32_e32 v81, v81
	s_add_i32 s6, s31, 0x2000
	s_cmpk_lg_i32 s31, 0x4000
	s_mov_b32 s24, s76
	s_cselect_b32 s76, s6, 0
	s_add_i32 s26, s26, 2
	s_cmp_gt_i32 s26, s91
	s_cbranch_scc1 .Lattn_exit
	s_waitcnt vmcnt(2) lgkmcnt(0)
	s_barrier
.Lattn_cpB:
	s_mov_b32 s4, s76
	s_mov_b32 s5, s26
	s_mov_b32 s25, s31
	ds_read_b64_tr_b16 v[52:53], v201 offset:24576
	ds_read_b64_tr_b16 v[54:55], v201 offset:25088
	v_mfma_f32_32x32x16_bf16 v[114:129], v[190:193], v[150:153], v[34:49]
	v_add_f32_e32 v50, v82, v50
	v_add_f32_e32 v194, v83, v194
	v_add_f32_e32 v195, v84, v195
	v_add_f32_e32 v196, v85, v196
	v_add_f32_e32 v50, v86, v50
	v_add_f32_e32 v194, v87, v194
	v_cvt_pk_bf16_f32 v158, v82, v83
	v_cvt_pk_bf16_f32 v159, v84, v85
	ds_read_b64_tr_b16 v[60:61], v201 offset:28672
	ds_read_b64_tr_b16 v[62:63], v201 offset:29184
	v_mfma_f32_32x32x16_bf16 v[98:113], v[186:189], v[150:153], v[34:49]
	v_add_f32_e32 v195, v88, v195
	v_add_f32_e32 v196, v89, v196
	v_add_f32_e32 v50, v90, v50
	v_add_f32_e32 v194, v91, v194
	v_cvt_pk_bf16_f32 v160, v86, v87
	v_cvt_pk_bf16_f32 v161, v88, v89
	ds_read_b64_tr_b16 v[82:83], v201 offset:25600
	ds_read_b64_tr_b16 v[84:85], v201 offset:26112
	v_mfma_f32_32x32x16_bf16 v[114:129], v[182:185], v[138:141], v[114:129]
	v_add_f32_e32 v195, v92, v195
	v_add_f32_e32 v196, v93, v196
	v_add_f32_e32 v50, v94, v50
	v_add_f32_e32 v194, v95, v194
	v_cvt_pk_bf16_f32 v154, v90, v91
	v_cvt_pk_bf16_f32 v155, v92, v93
	ds_read_b64_tr_b16 v[86:87], v201 offset:29696
	ds_read_b64_tr_b16 v[88:89], v201 offset:30208
	v_mfma_f32_32x32x16_bf16 v[98:113], v[178:181], v[138:141], v[98:113]
	v_add_f32_e32 v195, v96, v195
	v_add_f32_e32 v196, v97, v196
	v_add_f32_e32 v50, v66, v50
	v_add_f32_e32 v194, v67, v194
	v_cvt_pk_bf16_f32 v156, v94, v95
	v_cvt_pk_bf16_f32 v157, v96, v97
	ds_read_b64_tr_b16 v[90:91], v201 offset:26624
	ds_read_b64_tr_b16 v[92:93], v201 offset:27136
	v_mfma_f32_32x32x16_bf16 v[114:129], v[174:177], v[134:137], v[114:129]
	v_add_f32_e32 v195, v68, v195
	v_add_f32_e32 v196, v69, v196
	v_add_f32_e32 v50, v70, v50
	v_add_f32_e32 v194, v71, v194
	v_cvt_pk_bf16_f32 v146, v66, v67
	v_cvt_pk_bf16_f32 v147, v68, v69
	ds_read_b64_tr_b16 v[64:65], v201 offset:30720
	ds_read_b64_tr_b16 v[66:67], v201 offset:31232
	v_mfma_f32_32x32x16_bf16 v[98:113], v[170:173], v[134:137], v[98:113]
	v_add_f32_e32 v195, v72, v195
	v_add_f32_e32 v196, v73, v196
	v_add_f32_e32 v50, v74, v50
	v_add_f32_e32 v194, v75, v194
	v_cvt_pk_bf16_f32 v148, v70, v71
	v_cvt_pk_bf16_f32 v149, v72, v73
	ds_read_b64_tr_b16 v[68:69], v201 offset:27648
	ds_read_b64_tr_b16 v[70:71], v201 offset:28160
	v_mfma_f32_32x32x16_bf16 v[114:129], v[166:169], v[130:133], v[114:129]
	v_add_f32_e32 v195, v76, v195
	v_add_f32_e32 v196, v77, v196
	v_add_f32_e32 v50, v78, v50
	v_add_f32_e32 v194, v79, v194
	v_cvt_pk_bf16_f32 v142, v74, v75
	v_cvt_pk_bf16_f32 v143, v76, v77
	ds_read_b64_tr_b16 v[72:73], v201 offset:31744
	ds_read_b64_tr_b16 v[74:75], v201 offset:32256
	v_mfma_f32_32x32x16_bf16 v[98:113], v[162:165], v[130:133], v[98:113]
	v_add_f32_e32 v195, v80, v195
	v_add_f32_e32 v196, v81, v196
	v_cvt_pk_bf16_f32 v144, v78, v79
	v_cvt_pk_bf16_f32 v145, v80, v81
	s_add_i32 s6, s31, s70
	s_mov_b32 s7, m0
	s_mov_b32 m0, s6
	s_nop 0
	global_load_lds_dwordx4 v197, s[98:99]
	s_mov_b32 m0, s7
	s_add_i32 s6, s76, s71
	s_mov_b32 s7, m0
	s_mov_b32 m0, s6
	s_nop 0
	global_load_lds_dwordx4 v197, s[100:101]
	s_mov_b32 m0, s7
	s_add_u32 s98, s98, 0x2000
	s_addc_u32 s99, s99, 0
	s_add_u32 s100, s100, 0x2000
	s_addc_u32 s101, s101, 0
	s_waitcnt lgkmcnt(14)
	v_mfma_f32_32x32x16_bf16 v[2:17], v[158:161], v[52:55], v[2:17]
	v_exp_f32_e32 v114, v114
	v_exp_f32_e32 v115, v115
	v_exp_f32_e32 v116, v116
	v_exp_f32_e32 v117, v117
	s_waitcnt lgkmcnt(12)
	v_mfma_f32_32x32x16_bf16 v[18:33], v[158:161], v[60:63], v[18:33]
	v_exp_f32_e32 v118, v118
	v_exp_f32_e32 v119, v119
	v_exp_f32_e32 v120, v120
	v_exp_f32_e32 v121, v121
	ds_read_b128 v[60:63], v203
	ds_read_b128 v[162:165], v203 offset:512
	s_waitcnt lgkmcnt(12)
	v_mfma_f32_32x32x16_bf16 v[2:17], v[154:157], v[82:85], v[2:17]
	v_exp_f32_e32 v122, v122
	v_exp_f32_e32 v123, v123
	v_exp_f32_e32 v124, v124
	v_exp_f32_e32 v125, v125
	ds_read_b128 v[166:169], v203 offset:2048
	ds_read_b128 v[170:173], v203 offset:2560
	s_waitcnt lgkmcnt(12)
	v_mfma_f32_32x32x16_bf16 v[18:33], v[154:157], v[86:89], v[18:33]
	v_exp_f32_e32 v126, v126
	v_exp_f32_e32 v127, v127
	v_exp_f32_e32 v128, v128
	v_exp_f32_e32 v129, v129
	ds_read_b128 v[174:177], v203 offset:4096
	ds_read_b128 v[178:181], v203 offset:4608
	s_waitcnt lgkmcnt(12)
	v_mfma_f32_32x32x16_bf16 v[2:17], v[146:149], v[90:93], v[2:17]
	v_exp_f32_e32 v98, v98
	v_exp_f32_e32 v99, v99
	v_exp_f32_e32 v100, v100
	v_exp_f32_e32 v101, v101
	ds_read_b128 v[182:185], v203 offset:6144
	ds_read_b128 v[52:55], v203 offset:6656
	s_waitcnt lgkmcnt(12)
	v_mfma_f32_32x32x16_bf16 v[18:33], v[146:149], v[64:67], v[18:33]
	v_exp_f32_e32 v102, v102
	v_exp_f32_e32 v103, v103
	v_exp_f32_e32 v104, v104
	v_exp_f32_e32 v105, v105
	s_waitcnt lgkmcnt(10)
	v_mfma_f32_32x32x16_bf16 v[2:17], v[142:145], v[68:71], v[2:17]
	v_exp_f32_e32 v106, v106
	v_exp_f32_e32 v107, v107
	v_exp_f32_e32 v108, v108
	v_exp_f32_e32 v109, v109
	s_waitcnt lgkmcnt(8)
	v_mfma_f32_32x32x16_bf16 v[18:33], v[142:145], v[72:75], v[18:33]
	v_exp_f32_e32 v110, v110
	v_exp_f32_e32 v111, v111
	v_exp_f32_e32 v112, v112
	v_exp_f32_e32 v113, v113
	s_waitcnt vmcnt(2) lgkmcnt(0)
	s_barrier
; #define WAIT_BAR(N) asm volatile("s_waitcnt vmcnt(" #N ") lgkmcnt(0)\n\ts_barrier":::"memory")
;   #define RESC() do{ if(resc){ asm volatile("s_waitcnt lgkmcnt(0)":::"memory"); \
;       _Pragma("unroll") for(int d_=0;d_<2;++d_) _Pragma("unroll") for(int r=0;r<16;++r)o[d_][r]*=wsf[crow(r,hi)]; } }while(0)
;   #define ROT() do{sl_prev=sl_cur;sl_cur=sl_next;sl_next=(sl_next==(NSLOT-1)*SLOTB)?0:sl_next+SLOTB;}while(0)
; template<int THRL> __device__ __forceinline__ void attn_unit(const bf16*Qu,const bf16*__restrict__ Kh,const bf16*__restrict__ Vh,bf16*Ou,const int NT,const float shift,char*shm){
;     ...
;   int t=1;
;     ...
;   for(;t+5<NT;t+=2){
;     STEP(pB0,pB1,pA0,pA1,t,true,true,true);     WAIT_BAR(2); RESC(); ROT();
	s_add_i32 s6, s76, 0x2000
	s_cmpk_lg_i32 s76, 0x4000
	s_cselect_b32 s31, s6, 0
	ds_read_b64_tr_b16 v[186:187], v199 offset:24576
	ds_read_b64_tr_b16 v[188:189], v199 offset:25088
	v_mfma_f32_32x32x16_bf16 v[82:97], v[60:63], v[150:153], v[34:49]
	v_add_f32_e32 v50, v114, v50
	v_add_f32_e32 v194, v115, v194
	v_add_f32_e32 v195, v116, v195
	v_add_f32_e32 v196, v117, v196
	v_add_f32_e32 v50, v118, v50
	v_add_f32_e32 v194, v119, v194
	v_cvt_pk_bf16_f32 v158, v114, v115
	v_cvt_pk_bf16_f32 v159, v116, v117
	ds_read_b64_tr_b16 v[60:61], v199 offset:28672
	ds_read_b64_tr_b16 v[62:63], v199 offset:29184
	v_mfma_f32_32x32x16_bf16 v[66:81], v[162:165], v[150:153], v[34:49]
	v_add_f32_e32 v195, v120, v195
	v_add_f32_e32 v196, v121, v196
	v_add_f32_e32 v50, v122, v50
	v_add_f32_e32 v194, v123, v194
	v_cvt_pk_bf16_f32 v160, v118, v119
	v_cvt_pk_bf16_f32 v161, v120, v121
	ds_read_b64_tr_b16 v[114:115], v199 offset:25600
	ds_read_b64_tr_b16 v[116:117], v199 offset:26112
	v_mfma_f32_32x32x16_bf16 v[82:97], v[166:169], v[138:141], v[82:97]
	v_add_f32_e32 v195, v124, v195
	v_add_f32_e32 v196, v125, v196
	v_add_f32_e32 v50, v126, v50
	v_add_f32_e32 v194, v127, v194
	v_cvt_pk_bf16_f32 v154, v122, v123
	v_cvt_pk_bf16_f32 v155, v124, v125
	ds_read_b64_tr_b16 v[118:119], v199 offset:29696
	ds_read_b64_tr_b16 v[120:121], v199 offset:30208
	v_mfma_f32_32x32x16_bf16 v[66:81], v[170:173], v[138:141], v[66:81]
	v_add_f32_e32 v195, v128, v195
	v_add_f32_e32 v196, v129, v196
	v_add_f32_e32 v50, v98, v50
	v_add_f32_e32 v194, v99, v194
	v_cvt_pk_bf16_f32 v156, v126, v127
	v_cvt_pk_bf16_f32 v157, v128, v129
	ds_read_b64_tr_b16 v[122:123], v199 offset:26624
	ds_read_b64_tr_b16 v[124:125], v199 offset:27136
	v_mfma_f32_32x32x16_bf16 v[82:97], v[174:177], v[134:137], v[82:97]
	v_add_f32_e32 v195, v100, v195
	v_add_f32_e32 v196, v101, v196
	v_add_f32_e32 v50, v102, v50
	v_add_f32_e32 v194, v103, v194
	v_cvt_pk_bf16_f32 v146, v98, v99
	v_cvt_pk_bf16_f32 v147, v100, v101
	ds_read_b64_tr_b16 v[98:99], v199 offset:30720
	ds_read_b64_tr_b16 v[100:101], v199 offset:31232
	v_mfma_f32_32x32x16_bf16 v[66:81], v[178:181], v[134:137], v[66:81]
	v_add_f32_e32 v195, v104, v195
	v_add_f32_e32 v196, v105, v196
	v_add_f32_e32 v50, v106, v50
	v_add_f32_e32 v194, v107, v194
	v_cvt_pk_bf16_f32 v148, v102, v103
	v_cvt_pk_bf16_f32 v149, v104, v105
	ds_read_b64_tr_b16 v[102:103], v199 offset:27648
	ds_read_b64_tr_b16 v[104:105], v199 offset:28160
	v_mfma_f32_32x32x16_bf16 v[82:97], v[182:185], v[130:133], v[82:97]
	v_add_f32_e32 v195, v108, v195
	v_add_f32_e32 v196, v109, v196
	v_add_f32_e32 v50, v110, v50
	v_add_f32_e32 v194, v111, v194
	v_cvt_pk_bf16_f32 v142, v106, v107
	v_cvt_pk_bf16_f32 v143, v108, v109
	ds_read_b64_tr_b16 v[106:107], v199 offset:31744
	ds_read_b64_tr_b16 v[108:109], v199 offset:32256
	v_mfma_f32_32x32x16_bf16 v[66:81], v[52:55], v[130:133], v[66:81]
	v_add_f32_e32 v195, v112, v195
	v_add_f32_e32 v196, v113, v196
	v_cvt_pk_bf16_f32 v144, v110, v111
	v_cvt_pk_bf16_f32 v145, v112, v113
	s_add_i32 s6, s76, s70
	s_mov_b32 s7, m0
	s_mov_b32 m0, s6
	s_nop 0
	global_load_lds_dwordx4 v197, s[98:99]
	s_mov_b32 m0, s7
	s_add_i32 s6, s31, s71
	s_mov_b32 s7, m0
	s_mov_b32 m0, s6
	s_nop 0
	global_load_lds_dwordx4 v197, s[100:101]
	s_mov_b32 m0, s7
	s_add_u32 s98, s98, 0x2000
	s_addc_u32 s99, s99, 0
	s_add_u32 s100, s100, 0x2000
	s_addc_u32 s101, s101, 0
	s_waitcnt lgkmcnt(14)
	v_mfma_f32_32x32x16_bf16 v[2:17], v[158:161], v[186:189], v[2:17]
	v_exp_f32_e32 v82, v82
	v_exp_f32_e32 v83, v83
	v_exp_f32_e32 v84, v84
	v_exp_f32_e32 v85, v85
	s_waitcnt lgkmcnt(12)
	v_mfma_f32_32x32x16_bf16 v[18:33], v[158:161], v[60:63], v[18:33]
	v_exp_f32_e32 v86, v86
	v_exp_f32_e32 v87, v87
	v_exp_f32_e32 v88, v88
	v_exp_f32_e32 v89, v89
	ds_read_b128 v[190:193], v204
	ds_read_b128 v[186:189], v204 offset:512
	s_waitcnt lgkmcnt(12)
	v_mfma_f32_32x32x16_bf16 v[2:17], v[154:157], v[114:117], v[2:17]
	v_exp_f32_e32 v90, v90
	v_exp_f32_e32 v91, v91
	v_exp_f32_e32 v92, v92
	v_exp_f32_e32 v93, v93
	ds_read_b128 v[182:185], v204 offset:2048
	ds_read_b128 v[178:181], v204 offset:2560
	s_waitcnt lgkmcnt(12)
	v_mfma_f32_32x32x16_bf16 v[18:33], v[154:157], v[118:121], v[18:33]
	v_exp_f32_e32 v94, v94
	v_exp_f32_e32 v95, v95
	v_exp_f32_e32 v96, v96
	v_exp_f32_e32 v97, v97
	ds_read_b128 v[174:177], v204 offset:4096
	ds_read_b128 v[170:173], v204 offset:4608
	s_waitcnt lgkmcnt(12)
	v_mfma_f32_32x32x16_bf16 v[2:17], v[146:149], v[122:125], v[2:17]
	v_exp_f32_e32 v66, v66
	v_exp_f32_e32 v67, v67
	v_exp_f32_e32 v68, v68
	v_exp_f32_e32 v69, v69
	ds_read_b128 v[166:169], v204 offset:6144
	ds_read_b128 v[162:165], v204 offset:6656
	s_waitcnt lgkmcnt(12)
	v_mfma_f32_32x32x16_bf16 v[18:33], v[146:149], v[98:101], v[18:33]
	v_exp_f32_e32 v70, v70
	v_exp_f32_e32 v71, v71
	v_exp_f32_e32 v72, v72
	v_exp_f32_e32 v73, v73
	s_waitcnt lgkmcnt(10)
	v_mfma_f32_32x32x16_bf16 v[2:17], v[142:145], v[102:105], v[2:17]
	v_exp_f32_e32 v74, v74
	v_exp_f32_e32 v75, v75
	v_exp_f32_e32 v76, v76
	v_exp_f32_e32 v77, v77
	s_waitcnt lgkmcnt(8)
	v_mfma_f32_32x32x16_bf16 v[18:33], v[142:145], v[106:109], v[18:33]
	v_exp_f32_e32 v78, v78
	v_exp_f32_e32 v79, v79
	v_exp_f32_e32 v80, v80
	v_exp_f32_e32 v81, v81
	s_add_i32 s6, s31, 0x2000
	s_cmpk_lg_i32 s31, 0x4000
	s_mov_b32 s24, s76
	s_cselect_b32 s76, s6, 0
	s_add_i32 s26, s26, 2
	s_cmp_gt_i32 s26, s91
	s_cbranch_scc1 .Lattn_exit
	s_waitcnt vmcnt(2) lgkmcnt(0)
	s_barrier
.Lattn_cpC:
	s_mov_b32 s4, s76
	s_mov_b32 s5, s26
	s_mov_b32 s25, s31
	ds_read_b64_tr_b16 v[52:53], v200 offset:24576
	ds_read_b64_tr_b16 v[54:55], v200 offset:25088
	v_mfma_f32_32x32x16_bf16 v[114:129], v[190:193], v[150:153], v[34:49]
	v_add_f32_e32 v50, v82, v50
	v_add_f32_e32 v194, v83, v194
	v_add_f32_e32 v195, v84, v195
	v_add_f32_e32 v196, v85, v196
	v_add_f32_e32 v50, v86, v50
	v_add_f32_e32 v194, v87, v194
	v_cvt_pk_bf16_f32 v158, v82, v83
	v_cvt_pk_bf16_f32 v159, v84, v85
	ds_read_b64_tr_b16 v[60:61], v200 offset:28672
	ds_read_b64_tr_b16 v[62:63], v200 offset:29184
	v_mfma_f32_32x32x16_bf16 v[98:113], v[186:189], v[150:153], v[34:49]
	v_add_f32_e32 v195, v88, v195
	v_add_f32_e32 v196, v89, v196
	v_add_f32_e32 v50, v90, v50
	v_add_f32_e32 v194, v91, v194
	v_cvt_pk_bf16_f32 v160, v86, v87
	v_cvt_pk_bf16_f32 v161, v88, v89
	ds_read_b64_tr_b16 v[82:83], v200 offset:25600
	ds_read_b64_tr_b16 v[84:85], v200 offset:26112
	v_mfma_f32_32x32x16_bf16 v[114:129], v[182:185], v[138:141], v[114:129]
	v_add_f32_e32 v195, v92, v195
	v_add_f32_e32 v196, v93, v196
	v_add_f32_e32 v50, v94, v50
	v_add_f32_e32 v194, v95, v194
	v_cvt_pk_bf16_f32 v154, v90, v91
	v_cvt_pk_bf16_f32 v155, v92, v93
	ds_read_b64_tr_b16 v[86:87], v200 offset:29696
	ds_read_b64_tr_b16 v[88:89], v200 offset:30208
	v_mfma_f32_32x32x16_bf16 v[98:113], v[178:181], v[138:141], v[98:113]
	v_add_f32_e32 v195, v96, v195
	v_add_f32_e32 v196, v97, v196
	v_add_f32_e32 v50, v66, v50
	v_add_f32_e32 v194, v67, v194
	v_cvt_pk_bf16_f32 v156, v94, v95
	v_cvt_pk_bf16_f32 v157, v96, v97
	ds_read_b64_tr_b16 v[90:91], v200 offset:26624
	ds_read_b64_tr_b16 v[92:93], v200 offset:27136
	v_mfma_f32_32x32x16_bf16 v[114:129], v[174:177], v[134:137], v[114:129]
	v_add_f32_e32 v195, v68, v195
	v_add_f32_e32 v196, v69, v196
	v_add_f32_e32 v50, v70, v50
	v_add_f32_e32 v194, v71, v194
	v_cvt_pk_bf16_f32 v146, v66, v67
	v_cvt_pk_bf16_f32 v147, v68, v69
	ds_read_b64_tr_b16 v[64:65], v200 offset:30720
	ds_read_b64_tr_b16 v[66:67], v200 offset:31232
	v_mfma_f32_32x32x16_bf16 v[98:113], v[170:173], v[134:137], v[98:113]
	v_add_f32_e32 v195, v72, v195
	v_add_f32_e32 v196, v73, v196
	v_add_f32_e32 v50, v74, v50
	v_add_f32_e32 v194, v75, v194
	v_cvt_pk_bf16_f32 v148, v70, v71
	v_cvt_pk_bf16_f32 v149, v72, v73
	ds_read_b64_tr_b16 v[68:69], v200 offset:27648
	ds_read_b64_tr_b16 v[70:71], v200 offset:28160
	v_mfma_f32_32x32x16_bf16 v[114:129], v[166:169], v[130:133], v[114:129]
	v_add_f32_e32 v195, v76, v195
	v_add_f32_e32 v196, v77, v196
	v_add_f32_e32 v50, v78, v50
	v_add_f32_e32 v194, v79, v194
	v_cvt_pk_bf16_f32 v142, v74, v75
	v_cvt_pk_bf16_f32 v143, v76, v77
	ds_read_b64_tr_b16 v[72:73], v200 offset:31744
	ds_read_b64_tr_b16 v[74:75], v200 offset:32256
	v_mfma_f32_32x32x16_bf16 v[98:113], v[162:165], v[130:133], v[98:113]
	v_add_f32_e32 v195, v80, v195
	v_add_f32_e32 v196, v81, v196
	v_cvt_pk_bf16_f32 v144, v78, v79
	v_cvt_pk_bf16_f32 v145, v80, v81
	s_add_i32 s6, s31, s70
	s_mov_b32 s7, m0
	s_mov_b32 m0, s6
	s_nop 0
	global_load_lds_dwordx4 v197, s[98:99]
	s_mov_b32 m0, s7
	s_add_i32 s6, s76, s71
	s_mov_b32 s7, m0
	s_mov_b32 m0, s6
	s_nop 0
	global_load_lds_dwordx4 v197, s[100:101]
	s_mov_b32 m0, s7
	s_add_u32 s98, s98, 0x2000
	s_addc_u32 s99, s99, 0
	s_add_u32 s100, s100, 0x2000
	s_addc_u32 s101, s101, 0
	s_waitcnt lgkmcnt(14)
	v_mfma_f32_32x32x16_bf16 v[2:17], v[158:161], v[52:55], v[2:17]
	v_exp_f32_e32 v114, v114
	v_exp_f32_e32 v115, v115
	v_exp_f32_e32 v116, v116
	v_exp_f32_e32 v117, v117
	s_waitcnt lgkmcnt(12)
	v_mfma_f32_32x32x16_bf16 v[18:33], v[158:161], v[60:63], v[18:33]
	v_exp_f32_e32 v118, v118
	v_exp_f32_e32 v119, v119
	v_exp_f32_e32 v120, v120
	v_exp_f32_e32 v121, v121
	ds_read_b128 v[60:63], v202
	ds_read_b128 v[162:165], v202 offset:512
	s_waitcnt lgkmcnt(12)
	v_mfma_f32_32x32x16_bf16 v[2:17], v[154:157], v[82:85], v[2:17]
	v_exp_f32_e32 v122, v122
	v_exp_f32_e32 v123, v123
	v_exp_f32_e32 v124, v124
	v_exp_f32_e32 v125, v125
	ds_read_b128 v[166:169], v202 offset:2048
	ds_read_b128 v[170:173], v202 offset:2560
	s_waitcnt lgkmcnt(12)
	v_mfma_f32_32x32x16_bf16 v[18:33], v[154:157], v[86:89], v[18:33]
	v_exp_f32_e32 v126, v126
	v_exp_f32_e32 v127, v127
	v_exp_f32_e32 v128, v128
	v_exp_f32_e32 v129, v129
	ds_read_b128 v[174:177], v202 offset:4096
	ds_read_b128 v[178:181], v202 offset:4608
	s_waitcnt lgkmcnt(12)
	v_mfma_f32_32x32x16_bf16 v[2:17], v[146:149], v[90:93], v[2:17]
	v_exp_f32_e32 v98, v98
	v_exp_f32_e32 v99, v99
	v_exp_f32_e32 v100, v100
	v_exp_f32_e32 v101, v101
	ds_read_b128 v[182:185], v202 offset:6144
	ds_read_b128 v[52:55], v202 offset:6656
	s_waitcnt lgkmcnt(12)
	v_mfma_f32_32x32x16_bf16 v[18:33], v[146:149], v[64:67], v[18:33]
	v_exp_f32_e32 v102, v102
	v_exp_f32_e32 v103, v103
	v_exp_f32_e32 v104, v104
	v_exp_f32_e32 v105, v105
	s_waitcnt lgkmcnt(10)
	v_mfma_f32_32x32x16_bf16 v[2:17], v[142:145], v[68:71], v[2:17]
	v_exp_f32_e32 v106, v106
	v_exp_f32_e32 v107, v107
	v_exp_f32_e32 v108, v108
	v_exp_f32_e32 v109, v109
	s_waitcnt lgkmcnt(8)
	v_mfma_f32_32x32x16_bf16 v[18:33], v[142:145], v[72:75], v[18:33]
	v_exp_f32_e32 v110, v110
	v_exp_f32_e32 v111, v111
	v_exp_f32_e32 v112, v112
	v_exp_f32_e32 v113, v113
	s_waitcnt vmcnt(2) lgkmcnt(0)
	s_barrier
; #define WAIT_BAR(N) asm volatile("s_waitcnt vmcnt(" #N ") lgkmcnt(0)\n\ts_barrier":::"memory")
;   #define RESC() do{ if(resc){ asm volatile("s_waitcnt lgkmcnt(0)":::"memory"); \
;       _Pragma("unroll") for(int d_=0;d_<2;++d_) _Pragma("unroll") for(int r=0;r<16;++r)o[d_][r]*=wsf[crow(r,hi)]; } }while(0)
;   #define ROT() do{sl_prev=sl_cur;sl_cur=sl_next;sl_next=(sl_next==(NSLOT-1)*SLOTB)?0:sl_next+SLOTB;}while(0)
; template<int THRL> __device__ __forceinline__ void attn_unit(const bf16*Qu,const bf16*__restrict__ Kh,const bf16*__restrict__ Vh,bf16*Ou,const int NT,const float shift,char*shm){
;     ...
;   int t=1;
;     ...
;   for(;t+5<NT;t+=2){
;     STEP(pB0,pB1,pA0,pA1,t,true,true,true);     WAIT_BAR(2); RESC(); ROT();
;     STEP(pA0,pA1,pB0,pB1,t+1,true,true,true);   WAIT_BAR(2); RESC(); ROT();
	s_add_i32 s6, s76, 0x2000
	s_cmpk_lg_i32 s76, 0x4000
	s_cselect_b32 s31, s6, 0
	ds_read_b64_tr_b16 v[186:187], v201 offset:24576
	ds_read_b64_tr_b16 v[188:189], v201 offset:25088
	v_mfma_f32_32x32x16_bf16 v[82:97], v[60:63], v[150:153], v[34:49]
	v_add_f32_e32 v50, v114, v50
	v_add_f32_e32 v194, v115, v194
	v_add_f32_e32 v195, v116, v195
	v_add_f32_e32 v196, v117, v196
	v_add_f32_e32 v50, v118, v50
	v_add_f32_e32 v194, v119, v194
	v_cvt_pk_bf16_f32 v158, v114, v115
	v_cvt_pk_bf16_f32 v159, v116, v117
	ds_read_b64_tr_b16 v[60:61], v201 offset:28672
	ds_read_b64_tr_b16 v[62:63], v201 offset:29184
	v_mfma_f32_32x32x16_bf16 v[66:81], v[162:165], v[150:153], v[34:49]
	v_add_f32_e32 v195, v120, v195
	v_add_f32_e32 v196, v121, v196
	v_add_f32_e32 v50, v122, v50
	v_add_f32_e32 v194, v123, v194
	v_cvt_pk_bf16_f32 v160, v118, v119
	v_cvt_pk_bf16_f32 v161, v120, v121
	ds_read_b64_tr_b16 v[114:115], v201 offset:25600
	ds_read_b64_tr_b16 v[116:117], v201 offset:26112
	v_mfma_f32_32x32x16_bf16 v[82:97], v[166:169], v[138:141], v[82:97]
	v_add_f32_e32 v195, v124, v195
	v_add_f32_e32 v196, v125, v196
	v_add_f32_e32 v50, v126, v50
	v_add_f32_e32 v194, v127, v194
	v_cvt_pk_bf16_f32 v154, v122, v123
	v_cvt_pk_bf16_f32 v155, v124, v125
	ds_read_b64_tr_b16 v[118:119], v201 offset:29696
	ds_read_b64_tr_b16 v[120:121], v201 offset:30208
	v_mfma_f32_32x32x16_bf16 v[66:81], v[170:173], v[138:141], v[66:81]
	v_add_f32_e32 v195, v128, v195
	v_add_f32_e32 v196, v129, v196
	v_add_f32_e32 v50, v98, v50
	v_add_f32_e32 v194, v99, v194
	v_cvt_pk_bf16_f32 v156, v126, v127
	v_cvt_pk_bf16_f32 v157, v128, v129
	ds_read_b64_tr_b16 v[122:123], v201 offset:26624
	ds_read_b64_tr_b16 v[124:125], v201 offset:27136
	v_mfma_f32_32x32x16_bf16 v[82:97], v[174:177], v[134:137], v[82:97]
	v_add_f32_e32 v195, v100, v195
	v_add_f32_e32 v196, v101, v196
	v_add_f32_e32 v50, v102, v50
	v_add_f32_e32 v194, v103, v194
	v_cvt_pk_bf16_f32 v146, v98, v99
	v_cvt_pk_bf16_f32 v147, v100, v101
	ds_read_b64_tr_b16 v[98:99], v201 offset:30720
	ds_read_b64_tr_b16 v[100:101], v201 offset:31232
	v_mfma_f32_32x32x16_bf16 v[66:81], v[178:181], v[134:137], v[66:81]
	v_add_f32_e32 v195, v104, v195
	v_add_f32_e32 v196, v105, v196
	v_add_f32_e32 v50, v106, v50
	v_add_f32_e32 v194, v107, v194
	v_cvt_pk_bf16_f32 v148, v102, v103
	v_cvt_pk_bf16_f32 v149, v104, v105
	ds_read_b64_tr_b16 v[102:103], v201 offset:27648
	ds_read_b64_tr_b16 v[104:105], v201 offset:28160
	v_mfma_f32_32x32x16_bf16 v[82:97], v[182:185], v[130:133], v[82:97]
	v_add_f32_e32 v195, v108, v195
	v_add_f32_e32 v196, v109, v196
	v_add_f32_e32 v50, v110, v50
	v_add_f32_e32 v194, v111, v194
	v_cvt_pk_bf16_f32 v142, v106, v107
	v_cvt_pk_bf16_f32 v143, v108, v109
	ds_read_b64_tr_b16 v[106:107], v201 offset:31744
	ds_read_b64_tr_b16 v[108:109], v201 offset:32256
	v_mfma_f32_32x32x16_bf16 v[66:81], v[52:55], v[130:133], v[66:81]
	v_add_f32_e32 v195, v112, v195
	v_add_f32_e32 v196, v113, v196
	v_cvt_pk_bf16_f32 v144, v110, v111
	v_cvt_pk_bf16_f32 v145, v112, v113
	s_add_i32 s6, s76, s70
	s_mov_b32 s7, m0
	s_mov_b32 m0, s6
	s_nop 0
	global_load_lds_dwordx4 v197, s[98:99]
	s_mov_b32 m0, s7
	s_add_i32 s6, s31, s71
	s_mov_b32 s7, m0
	s_mov_b32 m0, s6
	s_nop 0
	global_load_lds_dwordx4 v197, s[100:101]
	s_mov_b32 m0, s7
	s_add_u32 s98, s98, 0x2000
	s_addc_u32 s99, s99, 0
	s_add_u32 s100, s100, 0x2000
	s_addc_u32 s101, s101, 0
	s_waitcnt lgkmcnt(14)
	v_mfma_f32_32x32x16_bf16 v[2:17], v[158:161], v[186:189], v[2:17]
	v_exp_f32_e32 v82, v82
	v_exp_f32_e32 v83, v83
	v_exp_f32_e32 v84, v84
	v_exp_f32_e32 v85, v85
	s_waitcnt lgkmcnt(12)
	v_mfma_f32_32x32x16_bf16 v[18:33], v[158:161], v[60:63], v[18:33]
	v_exp_f32_e32 v86, v86
	v_exp_f32_e32 v87, v87
	v_exp_f32_e32 v88, v88
	v_exp_f32_e32 v89, v89
	ds_read_b128 v[190:193], v203
	ds_read_b128 v[186:189], v203 offset:512
	s_waitcnt lgkmcnt(12)
	v_mfma_f32_32x32x16_bf16 v[2:17], v[154:157], v[114:117], v[2:17]
	v_exp_f32_e32 v90, v90
	v_exp_f32_e32 v91, v91
	v_exp_f32_e32 v92, v92
	v_exp_f32_e32 v93, v93
	ds_read_b128 v[182:185], v203 offset:2048
	ds_read_b128 v[178:181], v203 offset:2560
	s_waitcnt lgkmcnt(12)
	v_mfma_f32_32x32x16_bf16 v[18:33], v[154:157], v[118:121], v[18:33]
	v_exp_f32_e32 v94, v94
	v_exp_f32_e32 v95, v95
	v_exp_f32_e32 v96, v96
	v_exp_f32_e32 v97, v97
	ds_read_b128 v[174:177], v203 offset:4096
	ds_read_b128 v[170:173], v203 offset:4608
	s_waitcnt lgkmcnt(12)
	v_mfma_f32_32x32x16_bf16 v[2:17], v[146:149], v[122:125], v[2:17]
	v_exp_f32_e32 v66, v66
	v_exp_f32_e32 v67, v67
	v_exp_f32_e32 v68, v68
	v_exp_f32_e32 v69, v69
	ds_read_b128 v[166:169], v203 offset:6144
	ds_read_b128 v[162:165], v203 offset:6656
	s_waitcnt lgkmcnt(12)
	v_mfma_f32_32x32x16_bf16 v[18:33], v[146:149], v[98:101], v[18:33]
	v_exp_f32_e32 v70, v70
	v_exp_f32_e32 v71, v71
	v_exp_f32_e32 v72, v72
	v_exp_f32_e32 v73, v73
	s_waitcnt lgkmcnt(10)
	v_mfma_f32_32x32x16_bf16 v[2:17], v[142:145], v[102:105], v[2:17]
	v_exp_f32_e32 v74, v74
	v_exp_f32_e32 v75, v75
	v_exp_f32_e32 v76, v76
	v_exp_f32_e32 v77, v77
	s_waitcnt lgkmcnt(8)
	v_mfma_f32_32x32x16_bf16 v[18:33], v[142:145], v[106:109], v[18:33]
	v_exp_f32_e32 v78, v78
	v_exp_f32_e32 v79, v79
	v_exp_f32_e32 v80, v80
	v_exp_f32_e32 v81, v81
	s_add_i32 s6, s31, 0x2000
	s_cmpk_lg_i32 s31, 0x4000
	s_mov_b32 s24, s76
	s_cselect_b32 s76, s6, 0
	s_add_i32 s26, s26, 2
	s_cmp_gt_i32 s26, s91
	s_cbranch_scc0 .Lattn_rot
